# attn DQK=64 fast path: PV reordered k-major with softmax-finish VALU and row-max tree interleaved into MFMA gaps; V frag prefetch; slow path kept for bias/tail tiles
# speedup vs baseline: 1.0212x; 1.0212x over previous
; __device__ __forceinline__ void finishSM(f32x16& p0, f32x16& p1, float alpha, float& l_reg, bf16x8& pa0, bf16x8& pa1, bf16x8& pa2, bf16x8& pa3) {
; #pragma unroll
;   for (int r = 0; r < 16; ++r) p1[r] = __builtin_amdgcn_exp2f(p1[r]);
;   float ps = 0;
; #pragma unroll
;   for (int r = 0; r < 16; ++r) ps += p0[r];
; #pragma unroll
;   for (int r = 0; r < 16; ++r) ps += p1[r];
;   { auto rr = __builtin_amdgcn_permlane32_swap(__float_as_uint(ps), __float_as_uint(ps), false, false);
;     ps = __uint_as_float(rr[0]) + __uint_as_float(rr[1]); }
;   l_reg = l_reg * alpha + ps;
;     ...
;   PK4(p0, 0, pa0); PK4(p0, 8, pa1); PK4(p1, 0, pa2); PK4(p1, 8, pa3);
;     ...
; }
; template <int DQK> __device__ __forceinline__ void qkt(f32x16& p0, f32x16& p1, const char* Ks, const bf16x8* qr, int r32, int hi, const f32x16& negm) {
; #pragma unroll
;   for (int d0 = 0; d0 < DQK / 16; ++d0) { const int cb = (d0 * 16 + hi * 8) * 2;
;     const bf16x8 b0 = *reinterpret_cast<const bf16x8*>(Ks + (DQK == 128 ? KSWZ(r32, cb) : KSWZ64(r32, cb)));
;     const bf16x8 b1 = *reinterpret_cast<const bf16x8*>(Ks + (DQK == 128 ? KSWZ(32 + r32, cb) : KSWZ64(32 + r32, cb)));
;     if (d0 == 0) { p0 = __builtin_amdgcn_mfma_f32_32x32x16_bf16(b0, qr[0], negm, 0, 0, 0); p1 = __builtin_amdgcn_mfma_f32_32x32x16_bf16(b1, qr[0], negm, 0, 0, 0); }
;     else { p0 = __builtin_amdgcn_mfma_f32_32x32x16_bf16(b0, qr[d0], p0, 0, 0, 0); p1 = __builtin_amdgcn_mfma_f32_32x32x16_bf16(b1, qr[d0], p1, 0, 0, 0); } }
; }
; __device__ __forceinline__ int v_st(int k, int c) { const int kk = (k & ~0xC) | ((k & 4) << 1) | ((k & 8) >> 1); return ((kk >> 3) * 4 + (c >> 5)) * 512 + ((kk & 7) * 32 + (c & 31)) * 2; }
; __device__ __forceinline__ int v_rd_base(int lane) { return ((lane & 3) << 3) | (((lane >> 2) & 3) << 6) | (((lane >> 4) & 1) << 5) | (((lane >> 5) & 1) << 8); }
; template <int OFF> __device__ __forceinline__ s16x4 tr_read(int vb) {
;   s16x4 r; asm volatile("ds_read_b64_tr_b16 %0, %1 offset:%2" : "=&v"(r) : "v"(vb), "i"(OFF) : "memory"); return r;
; }
; template <int D0> __device__ __forceinline__ void pv_one(f32x16& od, int vb, bf16x8 pa0, bf16x8 pa1, bf16x8 pa2, bf16x8 pa3) {
;   const s16x4 l0 = tr_read<v_rd_off(D0, 0, 0)>(vb), h0 = tr_read<v_rd_off(D0, 0, 1)>(vb), l1 = tr_read<v_rd_off(D0, 1, 0)>(vb), h1 = tr_read<v_rd_off(D0, 1, 1)>(vb);
.Lcret_h1:
	s_add_i32 s99, s19, 0xffffff61
	s_cmp_lt_u32 s99, 0xfffffea3
	s_cbranch_scc0 .Lslow_h1
	s_cmp_le_u32 s18, s47
	s_cbranch_scc0 .Lslow_h1
	ds_read_b128 v[180:183], v225 offset:53248
	ds_read_b128 v[116:119], v225 offset:49152
	v_add_f32_e32 v0, 0, v148
	v_add_f32_e32 v0, v178, v0
	v_add_f32_e32 v0, v146, v0
	v_add_f32_e32 v0, v149, v0
	v_add_f32_e32 v0, v144, v0
	v_add_f32_e32 v0, v147, v0
	v_add_f32_e32 v0, v143, v0
	v_add_f32_e32 v0, v145, v0
	v_cvt_pk_bf16_f32 v76, v148, v178
	v_cvt_pk_bf16_f32 v77, v146, v149
	v_cvt_pk_bf16_f32 v78, v144, v147
	v_cvt_pk_bf16_f32 v79, v143, v145
	s_waitcnt lgkmcnt(0)
	v_mfma_f32_32x32x16_bf16 v[84:99], v[116:119], v[162:165], v[236:251]
	v_add_f32_e32 v0, v137, v0
	v_add_f32_e32 v0, v139, v0
	v_add_f32_e32 v0, v136, v0
	v_add_f32_e32 v0, v138, v0
	v_mfma_f32_32x32x16_bf16 v[116:131], v[180:183], v[162:165], v[236:251]
	ds_read_b128 v[180:183], v227 offset:53248
	ds_read_b128 v[184:187], v227 offset:49152
	v_add_f32_e32 v0, v135, v0
	v_add_f32_e32 v0, v142, v0
	v_add_f32_e32 v0, v140, v0
	v_add_f32_e32 v0, v141, v0
	v_cvt_pk_bf16_f32 v80, v137, v139
	v_cvt_pk_bf16_f32 v81, v136, v138
	s_waitcnt lgkmcnt(1)
	v_mfma_f32_32x32x16_bf16 v[116:131], v[180:183], v[158:161], v[116:131]
	v_cvt_pk_bf16_f32 v82, v135, v142
	v_cvt_pk_bf16_f32 v83, v140, v141
	v_permlane32_swap_b32_e32 v76, v78
	v_permlane32_swap_b32_e32 v77, v79
	v_lshl_add_u64 v[148:149], v[194:195], 0, s[0:1]
	s_waitcnt lgkmcnt(0)
	v_mfma_f32_32x32x16_bf16 v[84:99], v[184:187], v[158:161], v[84:99]
	ds_read_b128 v[180:183], v228 offset:53248
	ds_read_b128 v[184:187], v228 offset:49152
	v_lshl_add_u64 v[196:197], v[192:193], 0, s[0:1]
	v_permlane32_swap_b32_e32 v80, v82
	v_permlane32_swap_b32_e32 v81, v83
	s_mov_b32 s4, 0x102b1000
	v_add_co_u32_e64 v132, s[4:5], s4, v148
	s_waitcnt lgkmcnt(1)
	v_mfma_f32_32x32x16_bf16 v[116:131], v[180:183], v[154:157], v[116:131]
	v_addc_co_u32_e64 v133, s[4:5], 0, v149, s[4:5]
	s_mov_b32 s4, 0x102f9000
	v_add_co_u32_e64 v202, s[4:5], s4, v148
	s_waitcnt lgkmcnt(0)
	v_mfma_f32_32x32x16_bf16 v[84:99], v[184:187], v[154:157], v[84:99]
	ds_read_b128 v[180:183], v226 offset:53248
	ds_read_b128 v[184:187], v226 offset:49152
	v_addc_co_u32_e64 v203, s[4:5], 0, v149, s[4:5]
	s_mov_b32 s4, 0x102b0000
	v_add_co_u32_e64 v204, s[4:5], s4, v196
	ds_read_b64_tr_b16 v[134:135], v223 offset:0
	ds_read_b64_tr_b16 v[136:137], v223 offset:0x800
	ds_read_b64_tr_b16 v[138:139], v223 offset:0x200
	ds_read_b64_tr_b16 v[140:141], v223 offset:0xa00
	v_addc_co_u32_e64 v205, s[4:5], 0, v197, s[4:5]
	ds_read_b64_tr_b16 v[142:143], v223 offset:0x400
	ds_read_b64_tr_b16 v[144:145], v223 offset:0xc00
	ds_read_b64_tr_b16 v[198:199], v223 offset:0x600
	ds_read_b64_tr_b16 v[200:201], v223 offset:0xe00
	s_waitcnt lgkmcnt(9)
	v_mfma_f32_32x32x16_bf16 v[116:131], v[180:183], v[150:153], v[116:131]
	s_waitcnt lgkmcnt(8)
	v_mfma_f32_32x32x16_bf16 v[84:99], v[184:187], v[150:153], v[84:99]
	global_load_dwordx4 v[178:181], v[132:133], off
	global_load_dwordx4 v[182:185], v[202:203], off
	global_load_dwordx4 v[186:189], v[204:205], off offset:2048
	s_waitcnt lgkmcnt(6)
	v_mfma_f32_32x32x16_bf16 v[50:65], v[76:79], v[134:137], v[50:65]
	ds_read_b64_tr_b16 v[134:135], v223 offset:0x1000
	ds_read_b64_tr_b16 v[136:137], v223 offset:0x1800
	v_exp_f32_e32 v68, v100
	v_exp_f32_e32 v69, v101
	v_add_f32_e32 v0, v68, v0
	s_waitcnt lgkmcnt(6)
	v_mfma_f32_32x32x16_bf16 v[34:49], v[76:79], v[138:141], v[34:49]
	ds_read_b64_tr_b16 v[138:139], v223 offset:0x1200
	ds_read_b64_tr_b16 v[140:141], v223 offset:0x1a00
	v_exp_f32_e32 v70, v102
	v_add_f32_e32 v0, v69, v0
	v_exp_f32_e32 v71, v103
	v_add_f32_e32 v0, v70, v0
	s_waitcnt lgkmcnt(6)
	v_mfma_f32_32x32x16_bf16 v[18:33], v[76:79], v[142:145], v[18:33]
	ds_read_b64_tr_b16 v[142:143], v223 offset:0x1400
	ds_read_b64_tr_b16 v[144:145], v223 offset:0x1c00
	v_exp_f32_e32 v72, v104
	v_add_f32_e32 v0, v71, v0
	v_exp_f32_e32 v73, v105
	v_add_f32_e32 v0, v72, v0
	s_waitcnt lgkmcnt(6)
; __device__ __forceinline__ void finishSM(f32x16& p0, f32x16& p1, float alpha, float& l_reg, bf16x8& pa0, bf16x8& pa1, bf16x8& pa2, bf16x8& pa3) {
; #pragma unroll
;   for (int r = 0; r < 16; ++r) p1[r] = __builtin_amdgcn_exp2f(p1[r]);
;   float ps = 0;
; #pragma unroll
;   for (int r = 0; r < 16; ++r) ps += p0[r];
; #pragma unroll
;   for (int r = 0; r < 16; ++r) ps += p1[r];
;   { auto rr = __builtin_amdgcn_permlane32_swap(__float_as_uint(ps), __float_as_uint(ps), false, false);
;     ps = __uint_as_float(rr[0]) + __uint_as_float(rr[1]); }
;   l_reg = l_reg * alpha + ps;
;     ...
;   PK4(p0, 0, pa0); PK4(p0, 8, pa1); PK4(p1, 0, pa2); PK4(p1, 8, pa3);
;     ...
; }
; template <int DQK> __device__ __forceinline__ void qkt(f32x16& p0, f32x16& p1, const char* Ks, const bf16x8* qr, int r32, int hi, const f32x16& negm) {
; #pragma unroll
;   for (int d0 = 0; d0 < DQK / 16; ++d0) { const int cb = (d0 * 16 + hi * 8) * 2;
;     const bf16x8 b0 = *reinterpret_cast<const bf16x8*>(Ks + (DQK == 128 ? KSWZ(r32, cb) : KSWZ64(r32, cb)));
;     const bf16x8 b1 = *reinterpret_cast<const bf16x8*>(Ks + (DQK == 128 ? KSWZ(32 + r32, cb) : KSWZ64(32 + r32, cb)));
;     if (d0 == 0) { p0 = __builtin_amdgcn_mfma_f32_32x32x16_bf16(b0, qr[0], negm, 0, 0, 0); p1 = __builtin_amdgcn_mfma_f32_32x32x16_bf16(b1, qr[0], negm, 0, 0, 0); }
;     else { p0 = __builtin_amdgcn_mfma_f32_32x32x16_bf16(b0, qr[d0], p0, 0, 0, 0); p1 = __builtin_amdgcn_mfma_f32_32x32x16_bf16(b1, qr[d0], p1, 0, 0, 0); } }
; }
; __device__ __forceinline__ int v_st(int k, int c) { const int kk = (k & ~0xC) | ((k & 4) << 1) | ((k & 8) >> 1); return ((kk >> 3) * 4 + (c >> 5)) * 512 + ((kk & 7) * 32 + (c & 31)) * 2; }
; __device__ __forceinline__ int v_rd_base(int lane) { return ((lane & 3) << 3) | (((lane >> 2) & 3) << 6) | (((lane >> 4) & 1) << 5) | (((lane >> 5) & 1) << 8); }
; template <int OFF> __device__ __forceinline__ s16x4 tr_read(int vb) {
;   s16x4 r; asm volatile("ds_read_b64_tr_b16 %0, %1 offset:%2" : "=&v"(r) : "v"(vb), "i"(OFF) : "memory"); return r;
; }
; template <int D0> __device__ __forceinline__ void pv_one(f32x16& od, int vb, bf16x8 pa0, bf16x8 pa1, bf16x8 pa2, bf16x8 pa3) {
;   const s16x4 l0 = tr_read<v_rd_off(D0, 0, 0)>(vb), h0 = tr_read<v_rd_off(D0, 0, 1)>(vb), l1 = tr_read<v_rd_off(D0, 1, 0)>(vb), h1 = tr_read<v_rd_off(D0, 1, 1)>(vb);
	v_mfma_f32_32x32x16_bf16 v[2:17], v[76:79], v[198:201], v[2:17]
	ds_read_b64_tr_b16 v[198:199], v223 offset:0x1600
	ds_read_b64_tr_b16 v[200:201], v223 offset:0x1e00
	v_exp_f32_e32 v74, v106
	v_add_f32_e32 v0, v73, v0
	v_exp_f32_e32 v75, v107
	v_add_f32_e32 v0, v74, v0
	v_add_f32_e32 v0, v75, v0
	s_waitcnt lgkmcnt(6)
	v_mfma_f32_32x32x16_bf16 v[50:65], v[80:83], v[134:137], v[50:65]
	ds_read_b64_tr_b16 v[134:135], v223 offset:0x2000
	ds_read_b64_tr_b16 v[136:137], v223 offset:0x2800
	v_cvt_pk_bf16_f32 v100, v68, v69
	v_cvt_pk_bf16_f32 v101, v70, v71
	v_cvt_pk_bf16_f32 v102, v72, v73
	v_cvt_pk_bf16_f32 v103, v74, v75
	s_waitcnt lgkmcnt(6)
	v_mfma_f32_32x32x16_bf16 v[34:49], v[80:83], v[138:141], v[34:49]
	ds_read_b64_tr_b16 v[138:139], v223 offset:0x2200
	ds_read_b64_tr_b16 v[140:141], v223 offset:0x2a00
	v_exp_f32_e32 v68, v108
	v_exp_f32_e32 v69, v109
	v_permlane32_swap_b32_e32 v100, v102
	v_permlane32_swap_b32_e32 v101, v103
	s_waitcnt lgkmcnt(6)
	v_mfma_f32_32x32x16_bf16 v[18:33], v[80:83], v[142:145], v[18:33]
	ds_read_b64_tr_b16 v[142:143], v223 offset:0x2400
	ds_read_b64_tr_b16 v[144:145], v223 offset:0x2c00
	v_exp_f32_e32 v70, v110
	v_exp_f32_e32 v71, v111
	v_exp_f32_e32 v72, v112
	s_waitcnt lgkmcnt(6)
	v_mfma_f32_32x32x16_bf16 v[2:17], v[80:83], v[198:201], v[2:17]
	ds_read_b64_tr_b16 v[198:199], v223 offset:0x2600
	ds_read_b64_tr_b16 v[200:201], v223 offset:0x2e00
	v_exp_f32_e32 v73, v113
	v_exp_f32_e32 v74, v114
	v_exp_f32_e32 v75, v115
	s_waitcnt lgkmcnt(6)
	v_mfma_f32_32x32x16_bf16 v[50:65], v[100:103], v[134:137], v[50:65]
	ds_read_b64_tr_b16 v[134:135], v223 offset:0x3000
	ds_read_b64_tr_b16 v[136:137], v223 offset:0x3800
	v_add_f32_e32 v0, v68, v0
	v_add_f32_e32 v0, v69, v0
	v_add_f32_e32 v0, v70, v0
	v_add_f32_e32 v0, v71, v0
	s_waitcnt lgkmcnt(6)
	v_mfma_f32_32x32x16_bf16 v[34:49], v[100:103], v[138:141], v[34:49]
	ds_read_b64_tr_b16 v[138:139], v223 offset:0x3200
	ds_read_b64_tr_b16 v[140:141], v223 offset:0x3a00
	v_add_f32_e32 v0, v72, v0
	v_add_f32_e32 v0, v73, v0
	v_add_f32_e32 v0, v74, v0
	v_add_f32_e32 v0, v75, v0
	v_mov_b32_e32 v231, v0
	s_waitcnt lgkmcnt(6)
	v_mfma_f32_32x32x16_bf16 v[18:33], v[100:103], v[142:145], v[18:33]
	ds_read_b64_tr_b16 v[142:143], v223 offset:0x3400
	ds_read_b64_tr_b16 v[144:145], v223 offset:0x3c00
	v_cvt_pk_bf16_f32 v104, v68, v69
	v_cvt_pk_bf16_f32 v105, v70, v71
	v_cvt_pk_bf16_f32 v106, v72, v73
	v_cvt_pk_bf16_f32 v107, v74, v75
	v_permlane32_swap_b32_e32 v0, v231
	s_waitcnt lgkmcnt(6)
	v_mfma_f32_32x32x16_bf16 v[2:17], v[100:103], v[198:201], v[2:17]
	ds_read_b64_tr_b16 v[198:199], v223 offset:0x3600
	ds_read_b64_tr_b16 v[200:201], v223 offset:0x3e00
	v_permlane32_swap_b32_e32 v104, v106
	v_permlane32_swap_b32_e32 v105, v107
	v_max_f32_e32 v132, v85, v85
	v_max_f32_e32 v133, v84, v84
	v_max_f32_e32 v132, v133, v132
	s_waitcnt lgkmcnt(6)
	v_mfma_f32_32x32x16_bf16 v[50:65], v[104:107], v[134:137], v[50:65]
	v_max3_f32 v132, v132, v86, v87
	v_max3_f32 v132, v132, v88, v89
	v_max3_f32 v132, v132, v90, v91
	v_max3_f32 v132, v132, v92, v93
	v_max3_f32 v132, v132, v94, v95
	s_waitcnt lgkmcnt(4)
	v_mfma_f32_32x32x16_bf16 v[34:49], v[104:107], v[138:141], v[34:49]
	v_max3_f32 v132, v132, v96, v97
	v_max3_f32 v132, v132, v98, v99
	v_max3_f32 v132, v132, v116, v117
	v_max3_f32 v132, v132, v118, v119
	v_max3_f32 v132, v132, v120, v121
	s_waitcnt lgkmcnt(2)
	v_mfma_f32_32x32x16_bf16 v[18:33], v[104:107], v[142:145], v[18:33]
	v_max3_f32 v132, v132, v122, v123
	v_max3_f32 v132, v132, v124, v125
	v_max3_f32 v132, v132, v126, v127
	v_max3_f32 v132, v132, v128, v129
	v_max3_f32 v132, v132, v130, v131
	s_waitcnt lgkmcnt(0)
	v_mfma_f32_32x32x16_bf16 v[2:17], v[104:107], v[198:201], v[2:17]
	v_mov_b32_e32 v133, v132
	s_nop 1
	v_permlane32_swap_b32_e32 v132, v133
	v_max_f32_e32 v133, v133, v133
	v_max_f32_e32 v132, v132, v132
	v_max_f32_e32 v100, v132, v133
	s_branch .Ljoin_h1

; template <bool FIRST> __device__ __forceinline__ void partialSM(f32x16& p0, f32x16& p1, float& m_reg, float& alpha, f32x16& negm, float c_cur) {
;     ...
;   alpha = 1.f;
;   if (FIRST || !__builtin_expect(__all(pmax <= THR2), 1)) {
;     const float d = FIRST ? pmax : fmaxf(pmax, 0.f); m_reg += d; if (!FIRST) alpha = __builtin_amdgcn_exp2f(-d);
.Ljoin_h1:
	v_cmp_ge_f32_e32 vcc, s30, v100
	s_cmp_lg_u64 vcc, exec
	s_cbranch_scc1 .LBB0_255

; __device__ __forceinline__ void finishSM(f32x16& p0, f32x16& p1, float alpha, float& l_reg, bf16x8& pa0, bf16x8& pa1, bf16x8& pa2, bf16x8& pa3) {
; #pragma unroll
;   for (int r = 0; r < 16; ++r) p1[r] = __builtin_amdgcn_exp2f(p1[r]);
;   float ps = 0;
; #pragma unroll
;   for (int r = 0; r < 16; ++r) ps += p0[r];
; #pragma unroll
;   for (int r = 0; r < 16; ++r) ps += p1[r];
;   { auto rr = __builtin_amdgcn_permlane32_swap(__float_as_uint(ps), __float_as_uint(ps), false, false);
;     ps = __uint_as_float(rr[0]) + __uint_as_float(rr[1]); }
;   l_reg = l_reg * alpha + ps;
;     ...
;   PK4(p0, 0, pa0); PK4(p0, 8, pa1); PK4(p1, 0, pa2); PK4(p1, 8, pa3);
;     ...
; }
; template <int DQK> __device__ __forceinline__ void qkt(f32x16& p0, f32x16& p1, const char* Ks, const bf16x8* qr, int r32, int hi, const f32x16& negm) {
; #pragma unroll
;   for (int d0 = 0; d0 < DQK / 16; ++d0) { const int cb = (d0 * 16 + hi * 8) * 2;
;     const bf16x8 b0 = *reinterpret_cast<const bf16x8*>(Ks + (DQK == 128 ? KSWZ(r32, cb) : KSWZ64(r32, cb)));
;     const bf16x8 b1 = *reinterpret_cast<const bf16x8*>(Ks + (DQK == 128 ? KSWZ(32 + r32, cb) : KSWZ64(32 + r32, cb)));
;     if (d0 == 0) { p0 = __builtin_amdgcn_mfma_f32_32x32x16_bf16(b0, qr[0], negm, 0, 0, 0); p1 = __builtin_amdgcn_mfma_f32_32x32x16_bf16(b1, qr[0], negm, 0, 0, 0); }
;     else { p0 = __builtin_amdgcn_mfma_f32_32x32x16_bf16(b0, qr[d0], p0, 0, 0, 0); p1 = __builtin_amdgcn_mfma_f32_32x32x16_bf16(b1, qr[d0], p1, 0, 0, 0); } }
; }
; __device__ __forceinline__ int v_st(int k, int c) { const int kk = (k & ~0xC) | ((k & 4) << 1) | ((k & 8) >> 1); return ((kk >> 3) * 4 + (c >> 5)) * 512 + ((kk & 7) * 32 + (c & 31)) * 2; }
; __device__ __forceinline__ int v_rd_base(int lane) { return ((lane & 3) << 3) | (((lane >> 2) & 3) << 6) | (((lane >> 4) & 1) << 5) | (((lane >> 5) & 1) << 8); }
; template <int OFF> __device__ __forceinline__ s16x4 tr_read(int vb) {
;   s16x4 r; asm volatile("ds_read_b64_tr_b16 %0, %1 offset:%2" : "=&v"(r) : "v"(vb), "i"(OFF) : "memory"); return r;
; }
; template <int D0> __device__ __forceinline__ void pv_one(f32x16& od, int vb, bf16x8 pa0, bf16x8 pa1, bf16x8 pa2, bf16x8 pa3) {
;   const s16x4 l0 = tr_read<v_rd_off(D0, 0, 0)>(vb), h0 = tr_read<v_rd_off(D0, 0, 1)>(vb), l1 = tr_read<v_rd_off(D0, 1, 0)>(vb), h1 = tr_read<v_rd_off(D0, 1, 1)>(vb);
.Lcret_h2:
	s_add_i32 s99, s19, 0xffffffa1
	s_cmp_lt_u32 s99, 0xfffffea3
	s_cbranch_scc0 .Lslow_h2
	s_add_i32 s99, s18, 64
	s_cmp_le_u32 s99, s47
	s_cbranch_scc0 .Lslow_h2
	ds_read_b128 v[84:87], v225 offset:36864
	ds_read_b128 v[116:119], v225 offset:32768
	v_add_f32_e32 v235, 0, v219
	v_add_f32_e32 v235, v233, v235
	v_add_f32_e32 v235, v209, v235
	v_add_f32_e32 v235, v220, v235
	v_add_f32_e32 v235, v207, v235
	v_add_f32_e32 v235, v218, v235
	v_add_f32_e32 v235, v206, v235
	v_add_f32_e32 v235, v208, v235
	v_cvt_pk_bf16_f32 v92, v219, v233
	v_cvt_pk_bf16_f32 v93, v209, v220
	v_cvt_pk_bf16_f32 v94, v207, v218
	v_cvt_pk_bf16_f32 v95, v206, v208
	s_waitcnt lgkmcnt(0)
	v_mfma_f32_32x32x16_bf16 v[68:83], v[116:119], v[162:165], v[236:251]
	v_add_f32_e32 v235, v203, v235
	v_add_f32_e32 v235, v205, v235
	v_add_f32_e32 v235, v201, v235
	v_add_f32_e32 v235, v204, v235
	v_mfma_f32_32x32x16_bf16 v[116:131], v[84:87], v[162:165], v[236:251]
	ds_read_b128 v[84:87], v227 offset:36864
	ds_read_b128 v[88:91], v227 offset:32768
	v_add_f32_e32 v235, v199, v235
	v_add_f32_e32 v235, v202, v235
	v_add_f32_e32 v235, v198, v235
	v_add_f32_e32 v235, v200, v235
	v_cvt_pk_bf16_f32 v96, v203, v205
	v_cvt_pk_bf16_f32 v97, v201, v204
	s_waitcnt lgkmcnt(1)
	v_mfma_f32_32x32x16_bf16 v[116:131], v[84:87], v[158:161], v[116:131]
	v_cvt_pk_bf16_f32 v98, v199, v202
	v_cvt_pk_bf16_f32 v99, v198, v200
	v_permlane32_swap_b32_e32 v92, v94
	v_permlane32_swap_b32_e32 v93, v95
	s_waitcnt lgkmcnt(0)
	v_mfma_f32_32x32x16_bf16 v[68:83], v[88:91], v[158:161], v[68:83]
	ds_read_b128 v[84:87], v228 offset:36864
	ds_read_b128 v[88:91], v228 offset:32768
	v_permlane32_swap_b32_e32 v96, v98
	v_permlane32_swap_b32_e32 v97, v99
	v_add_co_u32_e32 v132, vcc, 0x10341000, v148
	s_waitcnt lgkmcnt(1)
	v_mfma_f32_32x32x16_bf16 v[116:131], v[84:87], v[154:157], v[116:131]
	v_addc_co_u32_e32 v133, vcc, 0, v149, vcc
	v_add_co_u32_e32 v174, vcc, 0x10389000, v148
	s_waitcnt lgkmcnt(0)
	v_mfma_f32_32x32x16_bf16 v[68:83], v[88:91], v[154:157], v[68:83]
	ds_read_b128 v[84:87], v226 offset:36864
	ds_read_b128 v[88:91], v226 offset:32768
	v_addc_co_u32_e32 v175, vcc, 0, v149, vcc
	v_add_co_u32_e32 v176, vcc, 0x10340000, v196
	ds_read_b64_tr_b16 v[134:135], v211 offset:0
	ds_read_b64_tr_b16 v[136:137], v211 offset:0x800
	ds_read_b64_tr_b16 v[138:139], v211 offset:0x200
	ds_read_b64_tr_b16 v[140:141], v211 offset:0xa00
	v_addc_co_u32_e32 v177, vcc, 0, v197, vcc
	ds_read_b64_tr_b16 v[142:143], v211 offset:0x400
	ds_read_b64_tr_b16 v[144:145], v211 offset:0xc00
	ds_read_b64_tr_b16 v[146:147], v211 offset:0x600
	ds_read_b64_tr_b16 v[148:149], v211 offset:0xe00
	s_waitcnt lgkmcnt(9)
	v_mfma_f32_32x32x16_bf16 v[116:131], v[84:87], v[150:153], v[116:131]
	s_waitcnt lgkmcnt(8)
	v_mfma_f32_32x32x16_bf16 v[68:83], v[88:91], v[150:153], v[68:83]
	s_cmp_ge_u32 s4, s28
	s_cbranch_scc1 .Lnold_h2
	global_load_dwordx4 v[166:169], v[132:133], off
	global_load_dwordx4 v[170:173], v[174:175], off
	global_load_dwordx4 v[174:177], v[176:177], off offset:2048
; __device__ __forceinline__ void finishSM(f32x16& p0, f32x16& p1, float alpha, float& l_reg, bf16x8& pa0, bf16x8& pa1, bf16x8& pa2, bf16x8& pa3) {
; #pragma unroll
;   for (int r = 0; r < 16; ++r) p1[r] = __builtin_amdgcn_exp2f(p1[r]);
;   float ps = 0;
; #pragma unroll
;   for (int r = 0; r < 16; ++r) ps += p0[r];
; #pragma unroll
;   for (int r = 0; r < 16; ++r) ps += p1[r];
;   { auto rr = __builtin_amdgcn_permlane32_swap(__float_as_uint(ps), __float_as_uint(ps), false, false);
;     ps = __uint_as_float(rr[0]) + __uint_as_float(rr[1]); }
;   l_reg = l_reg * alpha + ps;
;     ...
;   PK4(p0, 0, pa0); PK4(p0, 8, pa1); PK4(p1, 0, pa2); PK4(p1, 8, pa3);
;     ...
; }
; template <int DQK> __device__ __forceinline__ void qkt(f32x16& p0, f32x16& p1, const char* Ks, const bf16x8* qr, int r32, int hi, const f32x16& negm) {
; #pragma unroll
;   for (int d0 = 0; d0 < DQK / 16; ++d0) { const int cb = (d0 * 16 + hi * 8) * 2;
;     const bf16x8 b0 = *reinterpret_cast<const bf16x8*>(Ks + (DQK == 128 ? KSWZ(r32, cb) : KSWZ64(r32, cb)));
;     const bf16x8 b1 = *reinterpret_cast<const bf16x8*>(Ks + (DQK == 128 ? KSWZ(32 + r32, cb) : KSWZ64(32 + r32, cb)));
;     if (d0 == 0) { p0 = __builtin_amdgcn_mfma_f32_32x32x16_bf16(b0, qr[0], negm, 0, 0, 0); p1 = __builtin_amdgcn_mfma_f32_32x32x16_bf16(b1, qr[0], negm, 0, 0, 0); }
;     else { p0 = __builtin_amdgcn_mfma_f32_32x32x16_bf16(b0, qr[d0], p0, 0, 0, 0); p1 = __builtin_amdgcn_mfma_f32_32x32x16_bf16(b1, qr[d0], p1, 0, 0, 0); } }
; }
; __device__ __forceinline__ int v_st(int k, int c) { const int kk = (k & ~0xC) | ((k & 4) << 1) | ((k & 8) >> 1); return ((kk >> 3) * 4 + (c >> 5)) * 512 + ((kk & 7) * 32 + (c & 31)) * 2; }
; __device__ __forceinline__ int v_rd_base(int lane) { return ((lane & 3) << 3) | (((lane >> 2) & 3) << 6) | (((lane >> 4) & 1) << 5) | (((lane >> 5) & 1) << 8); }
; template <int OFF> __device__ __forceinline__ s16x4 tr_read(int vb) {
;   s16x4 r; asm volatile("ds_read_b64_tr_b16 %0, %1 offset:%2" : "=&v"(r) : "v"(vb), "i"(OFF) : "memory"); return r;
; }
; template <int D0> __device__ __forceinline__ void pv_one(f32x16& od, int vb, bf16x8 pa0, bf16x8 pa1, bf16x8 pa2, bf16x8 pa3) {
;   const s16x4 l0 = tr_read<v_rd_off(D0, 0, 0)>(vb), h0 = tr_read<v_rd_off(D0, 0, 1)>(vb), l1 = tr_read<v_rd_off(D0, 1, 0)>(vb), h1 = tr_read<v_rd_off(D0, 1, 1)>(vb);
.Lnold_h2:
	s_addk_i32 s19, 0xffa1
	s_waitcnt lgkmcnt(6)
	v_mfma_f32_32x32x16_bf16 v[50:65], v[92:95], v[134:137], v[50:65]
	ds_read_b64_tr_b16 v[134:135], v211 offset:0x1000
	ds_read_b64_tr_b16 v[136:137], v211 offset:0x1800
	v_exp_f32_e32 v84, v100
	v_exp_f32_e32 v85, v101
	v_add_f32_e32 v235, v84, v235
	s_waitcnt lgkmcnt(6)
	v_mfma_f32_32x32x16_bf16 v[34:49], v[92:95], v[138:141], v[34:49]
	ds_read_b64_tr_b16 v[138:139], v211 offset:0x1200
	ds_read_b64_tr_b16 v[140:141], v211 offset:0x1a00
	v_exp_f32_e32 v86, v102
	v_add_f32_e32 v235, v85, v235
	v_exp_f32_e32 v87, v103
	v_add_f32_e32 v235, v86, v235
	s_waitcnt lgkmcnt(6)
	v_mfma_f32_32x32x16_bf16 v[18:33], v[92:95], v[142:145], v[18:33]
	ds_read_b64_tr_b16 v[142:143], v211 offset:0x1400
	ds_read_b64_tr_b16 v[144:145], v211 offset:0x1c00
	v_exp_f32_e32 v88, v104
	v_add_f32_e32 v235, v87, v235
	v_exp_f32_e32 v89, v105
	v_add_f32_e32 v235, v88, v235
	s_waitcnt lgkmcnt(6)
	v_mfma_f32_32x32x16_bf16 v[2:17], v[92:95], v[146:149], v[2:17]
	ds_read_b64_tr_b16 v[146:147], v211 offset:0x1600
	ds_read_b64_tr_b16 v[148:149], v211 offset:0x1e00
	v_exp_f32_e32 v90, v106
	v_add_f32_e32 v235, v89, v235
	v_exp_f32_e32 v91, v107
	v_add_f32_e32 v235, v90, v235
	v_add_f32_e32 v235, v91, v235
	s_waitcnt lgkmcnt(6)
	v_mfma_f32_32x32x16_bf16 v[50:65], v[96:99], v[134:137], v[50:65]
	ds_read_b64_tr_b16 v[134:135], v211 offset:0x2000
	ds_read_b64_tr_b16 v[136:137], v211 offset:0x2800
	v_cvt_pk_bf16_f32 v100, v84, v85
	v_cvt_pk_bf16_f32 v101, v86, v87
	v_cvt_pk_bf16_f32 v102, v88, v89
	v_cvt_pk_bf16_f32 v103, v90, v91
	s_waitcnt lgkmcnt(6)
	v_mfma_f32_32x32x16_bf16 v[34:49], v[96:99], v[138:141], v[34:49]
	ds_read_b64_tr_b16 v[138:139], v211 offset:0x2200
	ds_read_b64_tr_b16 v[140:141], v211 offset:0x2a00
	v_exp_f32_e32 v84, v108
	v_exp_f32_e32 v85, v109
	v_permlane32_swap_b32_e32 v100, v102
	v_permlane32_swap_b32_e32 v101, v103
	s_waitcnt lgkmcnt(6)
	v_mfma_f32_32x32x16_bf16 v[18:33], v[96:99], v[142:145], v[18:33]
	ds_read_b64_tr_b16 v[142:143], v211 offset:0x2400
	ds_read_b64_tr_b16 v[144:145], v211 offset:0x2c00
	v_exp_f32_e32 v86, v110
	v_exp_f32_e32 v87, v111
	v_exp_f32_e32 v88, v112
	s_waitcnt lgkmcnt(6)
	v_mfma_f32_32x32x16_bf16 v[2:17], v[96:99], v[146:149], v[2:17]
	ds_read_b64_tr_b16 v[146:147], v211 offset:0x2600
	ds_read_b64_tr_b16 v[148:149], v211 offset:0x2e00
	v_exp_f32_e32 v89, v113
	v_exp_f32_e32 v90, v114
	v_exp_f32_e32 v91, v115
	s_waitcnt lgkmcnt(6)
	v_mfma_f32_32x32x16_bf16 v[50:65], v[100:103], v[134:137], v[50:65]
	ds_read_b64_tr_b16 v[134:135], v211 offset:0x3000
	ds_read_b64_tr_b16 v[136:137], v211 offset:0x3800
	v_add_f32_e32 v235, v84, v235
	v_add_f32_e32 v235, v85, v235
	v_add_f32_e32 v235, v86, v235
	v_add_f32_e32 v235, v87, v235
	s_waitcnt lgkmcnt(6)
	v_mfma_f32_32x32x16_bf16 v[34:49], v[100:103], v[138:141], v[34:49]
	ds_read_b64_tr_b16 v[138:139], v211 offset:0x3200
	ds_read_b64_tr_b16 v[140:141], v211 offset:0x3a00
	v_add_f32_e32 v235, v88, v235
	v_add_f32_e32 v235, v89, v235
	v_add_f32_e32 v235, v90, v235
	v_add_f32_e32 v235, v91, v235
	v_mov_b32_e32 v252, v235
	s_waitcnt lgkmcnt(6)
	v_mfma_f32_32x32x16_bf16 v[18:33], v[100:103], v[142:145], v[18:33]
	ds_read_b64_tr_b16 v[142:143], v211 offset:0x3400
	ds_read_b64_tr_b16 v[144:145], v211 offset:0x3c00
	v_cvt_pk_bf16_f32 v104, v84, v85
	v_cvt_pk_bf16_f32 v105, v86, v87
	v_cvt_pk_bf16_f32 v106, v88, v89
	v_cvt_pk_bf16_f32 v107, v90, v91
	v_permlane32_swap_b32_e32 v235, v252
	s_waitcnt lgkmcnt(6)
	v_mfma_f32_32x32x16_bf16 v[2:17], v[100:103], v[146:149], v[2:17]
	ds_read_b64_tr_b16 v[146:147], v211 offset:0x3600
	ds_read_b64_tr_b16 v[148:149], v211 offset:0x3e00
	v_permlane32_swap_b32_e32 v104, v106
	v_permlane32_swap_b32_e32 v105, v107
	v_max_f32_e32 v132, v69, v69
	v_max_f32_e32 v133, v68, v68
	v_max_f32_e32 v132, v133, v132
	s_waitcnt lgkmcnt(6)
	v_mfma_f32_32x32x16_bf16 v[50:65], v[104:107], v[134:137], v[50:65]
	v_max3_f32 v132, v132, v70, v71
	v_max3_f32 v132, v132, v72, v73
	v_max3_f32 v132, v132, v74, v75
	v_max3_f32 v132, v132, v76, v77
	v_max3_f32 v132, v132, v78, v79
	s_waitcnt lgkmcnt(4)
	v_mfma_f32_32x32x16_bf16 v[34:49], v[104:107], v[138:141], v[34:49]
	v_max3_f32 v132, v132, v80, v81
	v_max3_f32 v132, v132, v82, v83
	v_max3_f32 v132, v132, v116, v117
	v_max3_f32 v132, v132, v118, v119
	v_max3_f32 v132, v132, v120, v121
	s_waitcnt lgkmcnt(2)
	v_mfma_f32_32x32x16_bf16 v[18:33], v[104:107], v[142:145], v[18:33]
	v_max3_f32 v132, v132, v122, v123
	v_max3_f32 v132, v132, v124, v125
	v_max3_f32 v132, v132, v126, v127
	v_max3_f32 v132, v132, v128, v129
	v_max3_f32 v132, v132, v130, v131
	s_waitcnt lgkmcnt(0)
	v_mfma_f32_32x32x16_bf16 v[2:17], v[104:107], v[146:149], v[2:17]
	v_mov_b32_e32 v133, v132
	s_nop 1
	v_permlane32_swap_b32_e32 v132, v133
	v_max_f32_e32 v133, v133, v133
	v_max_f32_e32 v132, v132, v132
	v_max_f32_e32 v196, v132, v133
	s_branch .Ljoin_h2

; template <bool FIRST> __device__ __forceinline__ void partialSM(f32x16& p0, f32x16& p1, float& m_reg, float& alpha, f32x16& negm, float c_cur) {
;     ...
;   alpha = 1.f;
;   if (FIRST || !__builtin_expect(__all(pmax <= THR2), 1)) {
;     const float d = FIRST ? pmax : fmaxf(pmax, 0.f); m_reg += d; if (!FIRST) alpha = __builtin_amdgcn_exp2f(-d);
.Ljoin_h2:
	v_cmp_ge_f32_e32 vcc, s30, v196
	s_cmp_lg_u64 vcc, exec
	s_cbranch_scc1 .LBB0_259

; __global__ void __launch_bounds__(NWAVES * 64) fwd_kernel(Args args) {
	.amdhsa_kernel _Z10fwd_kernel4Args
		.amdhsa_group_segment_fixed_size 0
		.amdhsa_private_segment_fixed_size 0
		.amdhsa_kernarg_size 416
		.amdhsa_user_sgpr_count 2
		.amdhsa_user_sgpr_dispatch_ptr 0
		.amdhsa_user_sgpr_queue_ptr 0
		.amdhsa_user_sgpr_kernarg_segment_ptr 1
		.amdhsa_user_sgpr_dispatch_id 0
		.amdhsa_user_sgpr_kernarg_preload_length 0
		.amdhsa_user_sgpr_kernarg_preload_offset 0
		.amdhsa_user_sgpr_private_segment_size 0
		.amdhsa_uses_dynamic_stack 0
		.amdhsa_enable_private_segment 0
		.amdhsa_system_sgpr_workgroup_id_x 1
		.amdhsa_system_sgpr_workgroup_id_y 0
		.amdhsa_system_sgpr_workgroup_id_z 0
		.amdhsa_system_sgpr_workgroup_info 0
		.amdhsa_system_vgpr_workitem_id 2
		.amdhsa_next_free_vgpr 256
		.amdhsa_next_free_sgpr 100
		.amdhsa_accum_offset 256
		.amdhsa_reserve_vcc 1
		.amdhsa_float_round_mode_32 0
		.amdhsa_float_round_mode_16_64 0
		.amdhsa_float_denorm_mode_32 3
		.amdhsa_float_denorm_mode_16_64 3
		.amdhsa_dx10_clamp 1
		.amdhsa_ieee_mode 1
		.amdhsa_fp16_overflow 0
		.amdhsa_tg_split 0
		.amdhsa_exception_fp_ieee_invalid_op 0
		.amdhsa_exception_fp_denorm_src 0
		.amdhsa_exception_fp_ieee_div_zero 0
		.amdhsa_exception_fp_ieee_overflow 0
		.amdhsa_exception_fp_ieee_underflow 0
		.amdhsa_exception_fp_ieee_inexact 0
		.amdhsa_exception_int_div_zero 0
	.end_amdhsa_kernel

; __global__ void __launch_bounds__(NWAVES * 64) fwd_kernel(Args args) {
amdhsa.kernels:
  - .agpr_count:     0
    .args:
      - .offset:         0
        .size:           160
        .value_kind:     by_value
      - .offset:         160
        .size:           4
        .value_kind:     hidden_block_count_x
      - .offset:         164
        .size:           4
        .value_kind:     hidden_block_count_y
      - .offset:         168
        .size:           4
        .value_kind:     hidden_block_count_z
      - .offset:         172
        .size:           2
        .value_kind:     hidden_group_size_x
      - .offset:         174
        .size:           2
        .value_kind:     hidden_group_size_y
      - .offset:         176
        .size:           2
        .value_kind:     hidden_group_size_z
      - .offset:         178
        .size:           2
        .value_kind:     hidden_remainder_x
      - .offset:         180
        .size:           2
        .value_kind:     hidden_remainder_y
      - .offset:         182
        .size:           2
        .value_kind:     hidden_remainder_z
      - .offset:         200
        .size:           8
        .value_kind:     hidden_global_offset_x
      - .offset:         208
        .size:           8
        .value_kind:     hidden_global_offset_y
      - .offset:         216
        .size:           8
        .value_kind:     hidden_global_offset_z
      - .offset:         224
        .size:           2
        .value_kind:     hidden_grid_dims
      - .offset:         248
        .size:           8
        .value_kind:     hidden_multigrid_sync_arg
      - .offset:         280
        .size:           4
        .value_kind:     hidden_dynamic_lds_size
    .group_segment_fixed_size: 0
    .kernarg_segment_align: 8
    .kernarg_segment_size: 416
    .language:       OpenCL C
    .language_version:
      - 2
      - 0
    .max_flat_workgroup_size: 512
    .name:           _Z10fwd_kernel4Args
    .private_segment_fixed_size: 0
    .sgpr_count:     106
    .sgpr_spill_count: 164
    .symbol:         _Z10fwd_kernel4Args.kd
    .uniform_work_group_size: 1
    .uses_dynamic_stack: false
    .vgpr_count:     256
    .vgpr_spill_count: 0
    .wavefront_size: 64
